# v16 plus 10 redundant post-barrier lgkmcnt(0) waits deleted in GEMM K-loops
# speedup vs baseline: 1.0034x; 1.0004x over previous
; #define PG8_STAGE(bufoff, gbase, voff) do { _Pragma("unroll") for (int _i = 0; _i < 2; ++_i) \
;         __builtin_amdgcn_global_load_lds((const unsigned*)((const char*)(gbase) + (voff)[_i]), (PG8_LAS unsigned*)(lds + (bufoff) + ldsw + _i * 8192), 16, 0, 0); } while (0)
; #define PG8_LDA(dst, b, h) do { _Pragma("unroll") for (int m = 0; m < 4; ++m) _Pragma("unroll") for (int k = 0; k < 2; ++k) dst[m][k] = *(const PG8_LAS bf16x8*)(lds + PG8_SA(b, h) + aoff + m * 2048 + k * 1024); } while (0)
; #define PG8_LDB(dst, b, h) do { _Pragma("unroll") for (int n = 0; n < 2; ++n) _Pragma("unroll") for (int k = 0; k < 2; ++k) dst[n][k] = *(const PG8_LAS bf16x8*)(lds + PG8_SB(b, h) + boff + n * 2048 + k * 1024); } while (0)
; #define PG8_MMA(ai, bj, At, Bt) do { __builtin_amdgcn_s_setprio(1); _Pragma("unroll") for (int m = 0; m < 4; ++m) _Pragma("unroll") for (int n = 0; n < 2; ++n) _Pragma("unroll") for (int k = 0; k < 2; ++k) \
;         acc[ai][bj][m][n] = __builtin_amdgcn_mfma_f32_16x16x32_bf16(Bt[n][k], At[m][k], acc[ai][bj][m][n], 0, 0, 0); __builtin_amdgcn_s_setprio(0); } while (0)
; #define PG8_WAIT_V(n) asm volatile("s_waitcnt vmcnt(" #n ")" ::: "memory")
; template <class Epi, class Sched, bool ALIGN_EPI = false, bool SP2 = false>
; __device__ __forceinline__ void gemm_phase(PG8_LAS unsigned char* lds, const Gemm g, const Sched& S, const Epi& E) {
;     ...
;         for (int t = 0; t < nt; t += 2) {
;             const bool last = (t == nt - 2);
;             const char* a1 = cA + (size_t)(t + 1) * kstep;
;             const char* a2 = last ? nA : cA + (size_t)(t + 2) * kstep; const char* b2 = last ? nB : cB + (size_t)(t + 2) * kstep;
;             const char* a3 = a2 + kstep; const char* b3 = b2 + kstep;
;             if (last && has_next) S.a_ready(nxt);
;             if constexpr (SP2) {
;             PG8_LDB(B0, 0, 0); PG8_LDB(B1, 0, 1); PG8_SCHED; PG8_LDA(At, 0, 0); PG8_STAGE(PG8_SA(1, 1), a1 + hstep, voffA);
;             PG8_WAIT_V(8); PG8_WAIT_L(0); PG8_BAR; PG8_MMA(0, 0, At, B0); if (doB1) PG8_MMA(0, 1, At, B1); PG8_BAR; PG8_SCHED;
;             PG8_LDA(At, 0, 1); PG8_STAGE(PG8_SB(0, 0), b2, voffB); PG8_STAGE(PG8_SB(0, 1), b2 + hstep, voffB); PG8_STAGE(PG8_SA(0, 0), a2, voffA);
;             PG8_WAIT_V(8); PG8_WAIT_L(0); PG8_BAR; if (doA1) { PG8_MMA(1, 0, At, B0); if (doB1) PG8_MMA(1, 1, At, B1); } PG8_BAR; PG8_SCHED;
.LBB0_269:
	s_add_u32 s52, s80, 0xfffc0080
	s_addc_u32 s53, s81, -1
	s_add_i32 s56, 0, 0x10000
	s_cmp_eq_u32 s55, 12
	s_cselect_b32 s61, s17, s53
	s_cselect_b32 s60, s38, s52
	v_add_u32_e32 v173, s56, v163
	s_cselect_b32 s53, s39, s54
	s_cselect_b32 s52, s50, s51
	s_add_i32 s59, 0, 0x14000
	ds_read_b128 v[158:161], v173
	ds_read_b128 v[174:177], v173 offset:1024
	ds_read_b128 v[178:181], v173 offset:2048
	ds_read_b128 v[182:185], v173 offset:3072
	v_add_u32_e32 v173, s59, v163
	ds_read_b128 v[186:189], v173
	ds_read_b128 v[190:193], v173 offset:1024
	ds_read_b128 v[194:197], v173 offset:2048
	ds_read_b128 v[198:201], v173 offset:3072
	v_lshl_add_u64 v[234:235], s[80:81], 0, v[152:153]
	s_add_i32 m0, s25, 0xc000
	ds_read_b128 v[202:205], v165
	ds_read_b128 v[206:209], v165 offset:1024
	ds_read_b128 v[214:217], v165 offset:2048
	ds_read_b128 v[218:221], v165 offset:3072
	ds_read_b128 v[222:225], v165 offset:4096
	ds_read_b128 v[226:229], v165 offset:5120
	ds_read_b128 v[230:233], v165 offset:6144
	ds_read_b128 v[246:249], v165 offset:7168
	global_load_lds_dwordx4 v[234:235], off
	v_lshl_add_u64 v[234:235], s[80:81], 0, v[154:155]
	s_add_i32 m0, s25, 0xe000
	s_nop 0
	global_load_lds_dwordx4 v[234:235], off
	s_waitcnt vmcnt(8)
	s_waitcnt lgkmcnt(0)
	s_barrier
	s_setprio 1
	v_mfma_f32_16x16x32_bf16 v[142:145], v[158:161], v[202:205], v[142:145]
	v_mfma_f32_16x16x32_bf16 v[138:141], v[178:181], v[202:205], v[138:141]
	v_mfma_f32_16x16x32_bf16 v[124:127], v[158:161], v[214:217], v[124:127]
	v_mfma_f32_16x16x32_bf16 v[120:123], v[178:181], v[214:217], v[120:123]
	v_mfma_f32_16x16x32_bf16 v[108:111], v[158:161], v[222:225], v[108:111]
	v_mfma_f32_16x16x32_bf16 v[104:107], v[178:181], v[222:225], v[104:107]
	v_mfma_f32_16x16x32_bf16 v[92:95], v[158:161], v[230:233], v[92:95]
	v_mfma_f32_16x16x32_bf16 v[88:91], v[178:181], v[230:233], v[88:91]
	v_mfma_f32_16x16x32_bf16 v[142:145], v[174:177], v[206:209], v[142:145]
	v_mfma_f32_16x16x32_bf16 v[138:141], v[182:185], v[206:209], v[138:141]
	v_mfma_f32_16x16x32_bf16 v[124:127], v[174:177], v[218:221], v[124:127]
	v_mfma_f32_16x16x32_bf16 v[120:123], v[182:185], v[218:221], v[120:123]
	v_mfma_f32_16x16x32_bf16 v[108:111], v[174:177], v[226:229], v[108:111]
	v_mfma_f32_16x16x32_bf16 v[104:107], v[182:185], v[226:229], v[104:107]
	v_mfma_f32_16x16x32_bf16 v[92:95], v[174:177], v[246:249], v[92:95]
	v_mfma_f32_16x16x32_bf16 v[88:91], v[182:185], v[246:249], v[88:91]
	s_setprio 0
	s_setprio 1
	v_mfma_f32_16x16x32_bf16 v[134:137], v[186:189], v[202:205], v[134:137]
	v_mfma_f32_16x16x32_bf16 v[130:133], v[194:197], v[202:205], v[130:133]
	v_mfma_f32_16x16x32_bf16 v[116:119], v[186:189], v[214:217], v[116:119]
	v_mfma_f32_16x16x32_bf16 v[112:115], v[194:197], v[214:217], v[112:115]
	v_mfma_f32_16x16x32_bf16 v[100:103], v[186:189], v[222:225], v[100:103]
	v_mfma_f32_16x16x32_bf16 v[96:99], v[194:197], v[222:225], v[96:99]
	v_mfma_f32_16x16x32_bf16 v[84:87], v[186:189], v[230:233], v[84:87]
	v_mfma_f32_16x16x32_bf16 v[80:83], v[194:197], v[230:233], v[80:83]
	v_mfma_f32_16x16x32_bf16 v[134:137], v[190:193], v[206:209], v[134:137]
	v_mfma_f32_16x16x32_bf16 v[130:133], v[198:201], v[206:209], v[130:133]
	v_mfma_f32_16x16x32_bf16 v[116:119], v[190:193], v[218:221], v[116:119]
	v_mfma_f32_16x16x32_bf16 v[112:115], v[198:201], v[218:221], v[112:115]
	v_mfma_f32_16x16x32_bf16 v[100:103], v[190:193], v[226:229], v[100:103]
	v_mfma_f32_16x16x32_bf16 v[96:99], v[198:201], v[226:229], v[96:99]
	v_mfma_f32_16x16x32_bf16 v[84:87], v[190:193], v[246:249], v[84:87]
	v_mfma_f32_16x16x32_bf16 v[80:83], v[198:201], v[246:249], v[80:83]
	s_setprio 0
	s_barrier
	s_add_i32 s56, s56, s22
	v_lshl_add_u64 v[234:235], s[52:53], 0, v[128:129]
	s_mov_b32 m0, s56
	ds_read_b128 v[202:205], v165 offset:16384
	ds_read_b128 v[206:209], v165 offset:17408
	ds_read_b128 v[214:217], v165 offset:18432
	ds_read_b128 v[218:221], v165 offset:19456
	ds_read_b128 v[222:225], v165 offset:20480
	ds_read_b128 v[226:229], v165 offset:21504
	ds_read_b128 v[230:233], v165 offset:22528
	ds_read_b128 v[246:249], v165 offset:23552
	global_load_lds_dwordx4 v[234:235], off
	s_add_i32 m0, s56, 0x2000
	s_add_u32 s56, s52, 0x40000
	v_lshl_add_u64 v[240:241], s[52:53], 0, v[146:147]
	s_addc_u32 s57, s53, 0
	s_add_i32 s59, s59, s22
	global_load_lds_dwordx4 v[240:241], off
	v_lshl_add_u64 v[250:251], s[56:57], 0, v[128:129]
	s_mov_b32 m0, s59
	v_lshl_add_u64 v[252:253], s[60:61], 0, v[148:149]
	global_load_lds_dwordx4 v[250:251], off
	v_lshl_add_u64 v[250:251], s[56:57], 0, v[146:147]
	s_add_i32 m0, s59, 0x2000
	s_nop 0
	global_load_lds_dwordx4 v[250:251], off
	v_lshl_add_u64 v[250:251], s[60:61], 0, v[150:151]
	s_mov_b32 m0, s25
	s_nop 0
	global_load_lds_dwordx4 v[250:251], off
	s_mov_b32 m0, s26
	s_nop 0
	global_load_lds_dwordx4 v[252:253], off
	s_waitcnt vmcnt(8)
	s_waitcnt lgkmcnt(0)
	s_barrier
; #define PG8_STAGE(bufoff, gbase, voff) do { _Pragma("unroll") for (int _i = 0; _i < 2; ++_i) \
;         __builtin_amdgcn_global_load_lds((const unsigned*)((const char*)(gbase) + (voff)[_i]), (PG8_LAS unsigned*)(lds + (bufoff) + ldsw + _i * 8192), 16, 0, 0); } while (0)
; #define PG8_LDA(dst, b, h) do { _Pragma("unroll") for (int m = 0; m < 4; ++m) _Pragma("unroll") for (int k = 0; k < 2; ++k) dst[m][k] = *(const PG8_LAS bf16x8*)(lds + PG8_SA(b, h) + aoff + m * 2048 + k * 1024); } while (0)
; #define PG8_LDB(dst, b, h) do { _Pragma("unroll") for (int n = 0; n < 2; ++n) _Pragma("unroll") for (int k = 0; k < 2; ++k) dst[n][k] = *(const PG8_LAS bf16x8*)(lds + PG8_SB(b, h) + boff + n * 2048 + k * 1024); } while (0)
; #define PG8_MMA(ai, bj, At, Bt) do { __builtin_amdgcn_s_setprio(1); _Pragma("unroll") for (int m = 0; m < 4; ++m) _Pragma("unroll") for (int n = 0; n < 2; ++n) _Pragma("unroll") for (int k = 0; k < 2; ++k) \
;         acc[ai][bj][m][n] = __builtin_amdgcn_mfma_f32_16x16x32_bf16(Bt[n][k], At[m][k], acc[ai][bj][m][n], 0, 0, 0); __builtin_amdgcn_s_setprio(0); } while (0)
; #define PG8_WAIT_V(n) asm volatile("s_waitcnt vmcnt(" #n ")" ::: "memory")
; #define PG8_WAIT_L(n) asm volatile("s_waitcnt lgkmcnt(" #n ")" ::: "memory")
; #define PG8_BAR __builtin_amdgcn_s_barrier()
; #define PG8_SCHED __builtin_amdgcn_sched_barrier(0)
; template <class Epi, class Sched, bool ALIGN_EPI = false, bool SP2 = false>
; __device__ __forceinline__ void gemm_phase(PG8_LAS unsigned char* lds, const Gemm g, const Sched& S, const Epi& E) {
;     ...
;             PG8_WAIT_V(8); PG8_WAIT_L(0); PG8_BAR; if (doA1) { PG8_MMA(1, 0, At, B0); if (doB1) PG8_MMA(1, 1, At, B1); } PG8_BAR; PG8_SCHED;
;             PG8_LDB(B0, 1, 0); PG8_LDB(B1, 1, 1); PG8_SCHED; PG8_LDA(At, 1, 0); PG8_STAGE(PG8_SA(0, 1), a2 + hstep, voffA);
;             PG8_WAIT_V(8); PG8_WAIT_L(0); PG8_BAR; PG8_MMA(0, 0, At, B0); if (doB1) PG8_MMA(0, 1, At, B1); PG8_BAR; PG8_SCHED;
	s_setprio 1
	v_mfma_f32_16x16x32_bf16 v[76:79], v[158:161], v[202:205], v[76:79]
	v_mfma_f32_16x16x32_bf16 v[72:75], v[178:181], v[202:205], v[72:75]
	v_mfma_f32_16x16x32_bf16 v[60:63], v[158:161], v[214:217], v[60:63]
	v_mfma_f32_16x16x32_bf16 v[56:59], v[178:181], v[214:217], v[56:59]
	v_mfma_f32_16x16x32_bf16 v[44:47], v[158:161], v[222:225], v[44:47]
	v_mfma_f32_16x16x32_bf16 v[40:43], v[178:181], v[222:225], v[40:43]
	v_mfma_f32_16x16x32_bf16 v[28:31], v[158:161], v[230:233], v[28:31]
	v_mfma_f32_16x16x32_bf16 v[24:27], v[178:181], v[230:233], v[24:27]
	v_mfma_f32_16x16x32_bf16 v[76:79], v[174:177], v[206:209], v[76:79]
	v_mfma_f32_16x16x32_bf16 v[72:75], v[182:185], v[206:209], v[72:75]
	v_mfma_f32_16x16x32_bf16 v[60:63], v[174:177], v[218:221], v[60:63]
	v_mfma_f32_16x16x32_bf16 v[56:59], v[182:185], v[218:221], v[56:59]
	v_mfma_f32_16x16x32_bf16 v[44:47], v[174:177], v[226:229], v[44:47]
	v_mfma_f32_16x16x32_bf16 v[40:43], v[182:185], v[226:229], v[40:43]
	v_mfma_f32_16x16x32_bf16 v[28:31], v[174:177], v[246:249], v[28:31]
	v_mfma_f32_16x16x32_bf16 v[24:27], v[182:185], v[246:249], v[24:27]
	s_setprio 0
	s_setprio 1
	v_mfma_f32_16x16x32_bf16 v[68:71], v[186:189], v[202:205], v[68:71]
	v_mfma_f32_16x16x32_bf16 v[64:67], v[194:197], v[202:205], v[64:67]
	v_mfma_f32_16x16x32_bf16 v[52:55], v[186:189], v[214:217], v[52:55]
	v_mfma_f32_16x16x32_bf16 v[48:51], v[194:197], v[214:217], v[48:51]
	v_mfma_f32_16x16x32_bf16 v[36:39], v[186:189], v[222:225], v[36:39]
	v_mfma_f32_16x16x32_bf16 v[32:35], v[194:197], v[222:225], v[32:35]
	v_mfma_f32_16x16x32_bf16 v[20:23], v[186:189], v[230:233], v[20:23]
	v_mfma_f32_16x16x32_bf16 v[16:19], v[194:197], v[230:233], v[16:19]
	v_mfma_f32_16x16x32_bf16 v[68:71], v[190:193], v[206:209], v[68:71]
	v_mfma_f32_16x16x32_bf16 v[64:67], v[198:201], v[206:209], v[64:67]
	v_mfma_f32_16x16x32_bf16 v[52:55], v[190:193], v[218:221], v[52:55]
	v_mfma_f32_16x16x32_bf16 v[48:51], v[198:201], v[218:221], v[48:51]
	v_mfma_f32_16x16x32_bf16 v[36:39], v[190:193], v[226:229], v[36:39]
	v_mfma_f32_16x16x32_bf16 v[32:35], v[198:201], v[226:229], v[32:35]
	v_mfma_f32_16x16x32_bf16 v[20:23], v[190:193], v[246:249], v[20:23]
	v_mfma_f32_16x16x32_bf16 v[16:19], v[198:201], v[246:249], v[16:19]
	s_setprio 0
	s_barrier
	s_add_i32 s59, 0, 0x18000
	v_add_u32_e32 v173, s59, v163
	s_add_i32 s63, 0, 0x1c000
	ds_read_b128 v[158:161], v173
	ds_read_b128 v[174:177], v173 offset:1024
	ds_read_b128 v[178:181], v173 offset:2048
	ds_read_b128 v[182:185], v173 offset:3072
	v_add_u32_e32 v173, s63, v163
	ds_read_b128 v[186:189], v173
	ds_read_b128 v[190:193], v173 offset:1024
	ds_read_b128 v[194:197], v173 offset:2048
	ds_read_b128 v[198:201], v173 offset:3072
	s_add_u32 s56, s60, 0x40000
	s_addc_u32 s57, s61, 0
	s_mov_b32 m0, s27
	v_lshl_add_u64 v[244:245], s[56:57], 0, v[150:151]
	ds_read_b128 v[202:205], v165 offset:32768
	ds_read_b128 v[206:209], v165 offset:33792
	ds_read_b128 v[214:217], v165 offset:34816
	ds_read_b128 v[218:221], v165 offset:35840
	ds_read_b128 v[222:225], v165 offset:36864
	ds_read_b128 v[226:229], v165 offset:37888
	ds_read_b128 v[230:233], v165 offset:38912
	ds_read_b128 v[246:249], v165 offset:39936
	global_load_lds_dwordx4 v[244:245], off
	v_lshl_add_u64 v[244:245], s[56:57], 0, v[148:149]
	s_mov_b32 m0, s28
	s_nop 0
	global_load_lds_dwordx4 v[244:245], off
	s_waitcnt vmcnt(8)
	s_waitcnt lgkmcnt(0)
	s_barrier
	s_setprio 1
	v_mfma_f32_16x16x32_bf16 v[142:145], v[158:161], v[202:205], v[142:145]
	v_mfma_f32_16x16x32_bf16 v[138:141], v[178:181], v[202:205], v[138:141]
	v_mfma_f32_16x16x32_bf16 v[124:127], v[158:161], v[214:217], v[124:127]
	v_mfma_f32_16x16x32_bf16 v[120:123], v[178:181], v[214:217], v[120:123]
	v_mfma_f32_16x16x32_bf16 v[108:111], v[158:161], v[222:225], v[108:111]
	v_mfma_f32_16x16x32_bf16 v[104:107], v[178:181], v[222:225], v[104:107]
	v_mfma_f32_16x16x32_bf16 v[92:95], v[158:161], v[230:233], v[92:95]
	v_mfma_f32_16x16x32_bf16 v[88:91], v[178:181], v[230:233], v[88:91]
	v_mfma_f32_16x16x32_bf16 v[142:145], v[174:177], v[206:209], v[142:145]
	v_mfma_f32_16x16x32_bf16 v[138:141], v[182:185], v[206:209], v[138:141]
	v_mfma_f32_16x16x32_bf16 v[124:127], v[174:177], v[218:221], v[124:127]
	v_mfma_f32_16x16x32_bf16 v[120:123], v[182:185], v[218:221], v[120:123]
	v_mfma_f32_16x16x32_bf16 v[108:111], v[174:177], v[226:229], v[108:111]
	v_mfma_f32_16x16x32_bf16 v[104:107], v[182:185], v[226:229], v[104:107]
	v_mfma_f32_16x16x32_bf16 v[92:95], v[174:177], v[246:249], v[92:95]
	v_mfma_f32_16x16x32_bf16 v[88:91], v[182:185], v[246:249], v[88:91]
	s_setprio 0
	s_setprio 1
	v_mfma_f32_16x16x32_bf16 v[134:137], v[186:189], v[202:205], v[134:137]
	v_mfma_f32_16x16x32_bf16 v[130:133], v[194:197], v[202:205], v[130:133]
	v_mfma_f32_16x16x32_bf16 v[116:119], v[186:189], v[214:217], v[116:119]
	v_mfma_f32_16x16x32_bf16 v[112:115], v[194:197], v[214:217], v[112:115]
	v_mfma_f32_16x16x32_bf16 v[100:103], v[186:189], v[222:225], v[100:103]
	v_mfma_f32_16x16x32_bf16 v[96:99], v[194:197], v[222:225], v[96:99]
	v_mfma_f32_16x16x32_bf16 v[84:87], v[186:189], v[230:233], v[84:87]
	v_mfma_f32_16x16x32_bf16 v[80:83], v[194:197], v[230:233], v[80:83]
	v_mfma_f32_16x16x32_bf16 v[134:137], v[190:193], v[206:209], v[134:137]
	v_mfma_f32_16x16x32_bf16 v[130:133], v[198:201], v[206:209], v[130:133]
	v_mfma_f32_16x16x32_bf16 v[116:119], v[190:193], v[218:221], v[116:119]
	v_mfma_f32_16x16x32_bf16 v[112:115], v[198:201], v[218:221], v[112:115]
	v_mfma_f32_16x16x32_bf16 v[100:103], v[190:193], v[226:229], v[100:103]
	v_mfma_f32_16x16x32_bf16 v[96:99], v[198:201], v[226:229], v[96:99]
	v_mfma_f32_16x16x32_bf16 v[84:87], v[190:193], v[246:249], v[84:87]
	v_mfma_f32_16x16x32_bf16 v[80:83], v[198:201], v[246:249], v[80:83]
	s_setprio 0
	s_barrier
; #define PG8_STAGE(bufoff, gbase, voff) do { _Pragma("unroll") for (int _i = 0; _i < 2; ++_i) \
;         __builtin_amdgcn_global_load_lds((const unsigned*)((const char*)(gbase) + (voff)[_i]), (PG8_LAS unsigned*)(lds + (bufoff) + ldsw + _i * 8192), 16, 0, 0); } while (0)
; #define PG8_LDA(dst, b, h) do { _Pragma("unroll") for (int m = 0; m < 4; ++m) _Pragma("unroll") for (int k = 0; k < 2; ++k) dst[m][k] = *(const PG8_LAS bf16x8*)(lds + PG8_SA(b, h) + aoff + m * 2048 + k * 1024); } while (0)
; #define PG8_MMA(ai, bj, At, Bt) do { __builtin_amdgcn_s_setprio(1); _Pragma("unroll") for (int m = 0; m < 4; ++m) _Pragma("unroll") for (int n = 0; n < 2; ++n) _Pragma("unroll") for (int k = 0; k < 2; ++k) \
;         acc[ai][bj][m][n] = __builtin_amdgcn_mfma_f32_16x16x32_bf16(Bt[n][k], At[m][k], acc[ai][bj][m][n], 0, 0, 0); __builtin_amdgcn_s_setprio(0); } while (0)
; #define PG8_WAIT_V(n) asm volatile("s_waitcnt vmcnt(" #n ")" ::: "memory")
; #define PG8_WAIT_L(n) asm volatile("s_waitcnt lgkmcnt(" #n ")" ::: "memory")
; #define PG8_BAR __builtin_amdgcn_s_barrier()
; #define PG8_SCHED __builtin_amdgcn_sched_barrier(0)
; template <class Epi, class Sched, bool ALIGN_EPI = false, bool SP2 = false>
; __device__ __forceinline__ void gemm_phase(PG8_LAS unsigned char* lds, const Gemm g, const Sched& S, const Epi& E) {
;     ...
;         for (int t = 0; t < nt; t += 2) {
;     ...
;             PG8_LDA(At, 1, 1); PG8_STAGE(PG8_SB(1, 0), b3, voffB); PG8_STAGE(PG8_SB(1, 1), b3 + hstep, voffB); PG8_STAGE(PG8_SA(1, 0), a3, voffA);
;             PG8_WAIT_V(8); PG8_WAIT_L(0); PG8_BAR; if (doA1) { PG8_MMA(1, 0, At, B0); if (doB1) PG8_MMA(1, 1, At, B1); } PG8_BAR; PG8_SCHED;
	s_add_i32 s56, s59, s22
	v_lshl_add_u64 v[234:235], v[234:235], 0, s[30:31]
	s_mov_b32 m0, s56
	ds_read_b128 v[202:205], v165 offset:49152
	ds_read_b128 v[206:209], v165 offset:50176
	ds_read_b128 v[214:217], v165 offset:51200
	ds_read_b128 v[218:221], v165 offset:52224
	ds_read_b128 v[222:225], v165 offset:53248
	ds_read_b128 v[226:229], v165 offset:54272
	ds_read_b128 v[230:233], v165 offset:55296
	ds_read_b128 v[246:249], v165 offset:56320
	global_load_lds_dwordx4 v[234:235], off
	s_add_i32 m0, s56, 0x2000
	s_add_u32 s52, s52, 0x40080
	v_lshl_add_u64 v[234:235], v[240:241], 0, s[30:31]
	s_addc_u32 s53, s53, 0
	s_add_i32 s56, s63, s22
	global_load_lds_dwordx4 v[234:235], off
	v_lshl_add_u64 v[234:235], s[52:53], 0, v[128:129]
	s_mov_b32 m0, s56
	s_nop 0
	global_load_lds_dwordx4 v[234:235], off
	v_lshl_add_u64 v[234:235], s[52:53], 0, v[146:147]
	s_add_i32 m0, s56, 0x2000
	s_nop 0
	global_load_lds_dwordx4 v[234:235], off
	v_lshl_add_u64 v[234:235], v[250:251], 0, s[30:31]
	s_mov_b32 m0, s33
	s_nop 0
	global_load_lds_dwordx4 v[234:235], off
	v_lshl_add_u64 v[234:235], v[252:253], 0, s[30:31]
	s_mov_b32 m0, s35
	s_nop 0
	global_load_lds_dwordx4 v[234:235], off
	s_waitcnt vmcnt(8)
	s_waitcnt lgkmcnt(0)
	s_barrier
	s_setprio 1
	v_mfma_f32_16x16x32_bf16 v[76:79], v[158:161], v[202:205], v[76:79]
	v_mfma_f32_16x16x32_bf16 v[72:75], v[178:181], v[202:205], v[72:75]
	v_mfma_f32_16x16x32_bf16 v[60:63], v[158:161], v[214:217], v[60:63]
	v_mfma_f32_16x16x32_bf16 v[56:59], v[178:181], v[214:217], v[56:59]
	v_mfma_f32_16x16x32_bf16 v[44:47], v[158:161], v[222:225], v[44:47]
	v_mfma_f32_16x16x32_bf16 v[40:43], v[178:181], v[222:225], v[40:43]
	v_mfma_f32_16x16x32_bf16 v[28:31], v[158:161], v[230:233], v[28:31]
	v_mfma_f32_16x16x32_bf16 v[24:27], v[178:181], v[230:233], v[24:27]
	v_mfma_f32_16x16x32_bf16 v[76:79], v[174:177], v[206:209], v[76:79]
	v_mfma_f32_16x16x32_bf16 v[72:75], v[182:185], v[206:209], v[72:75]
	v_mfma_f32_16x16x32_bf16 v[60:63], v[174:177], v[218:221], v[60:63]
	v_mfma_f32_16x16x32_bf16 v[56:59], v[182:185], v[218:221], v[56:59]
	v_mfma_f32_16x16x32_bf16 v[44:47], v[174:177], v[226:229], v[44:47]
	v_mfma_f32_16x16x32_bf16 v[40:43], v[182:185], v[226:229], v[40:43]
	v_mfma_f32_16x16x32_bf16 v[28:31], v[174:177], v[246:249], v[28:31]
	v_mfma_f32_16x16x32_bf16 v[24:27], v[182:185], v[246:249], v[24:27]
	s_setprio 0
	s_setprio 1
	v_mfma_f32_16x16x32_bf16 v[68:71], v[186:189], v[202:205], v[68:71]
	v_mfma_f32_16x16x32_bf16 v[64:67], v[194:197], v[202:205], v[64:67]
	v_mfma_f32_16x16x32_bf16 v[52:55], v[186:189], v[214:217], v[52:55]
	v_mfma_f32_16x16x32_bf16 v[48:51], v[194:197], v[214:217], v[48:51]
	v_mfma_f32_16x16x32_bf16 v[36:39], v[186:189], v[222:225], v[36:39]
	v_mfma_f32_16x16x32_bf16 v[32:35], v[194:197], v[222:225], v[32:35]
	v_mfma_f32_16x16x32_bf16 v[20:23], v[186:189], v[230:233], v[20:23]
	v_mfma_f32_16x16x32_bf16 v[16:19], v[194:197], v[230:233], v[16:19]
	v_mfma_f32_16x16x32_bf16 v[68:71], v[190:193], v[206:209], v[68:71]
	v_mfma_f32_16x16x32_bf16 v[64:67], v[198:201], v[206:209], v[64:67]
	v_mfma_f32_16x16x32_bf16 v[52:55], v[190:193], v[218:221], v[52:55]
	v_mfma_f32_16x16x32_bf16 v[48:51], v[198:201], v[218:221], v[48:51]
	v_mfma_f32_16x16x32_bf16 v[36:39], v[190:193], v[226:229], v[36:39]
	v_mfma_f32_16x16x32_bf16 v[32:35], v[198:201], v[226:229], v[32:35]
	v_mfma_f32_16x16x32_bf16 v[20:23], v[190:193], v[246:249], v[20:23]
	v_mfma_f32_16x16x32_bf16 v[16:19], v[198:201], v[246:249], v[16:19]
	s_setprio 0
	s_barrier
	s_add_i32 s55, s55, 2
	s_add_u32 s80, s80, 0x100
	s_addc_u32 s81, s81, 0
	s_add_u32 s51, s51, 0x100
	s_addc_u32 s54, s54, 0
	s_cmp_gt_u32 s55, 13
	s_cbranch_scc0 .LBB0_269
	s_and_b64 vcc, exec, s[20:21]
	s_cbranch_vccz .LBB0_272
	s_barrier

; #define PG8_STAGE(bufoff, gbase, voff) do { _Pragma("unroll") for (int _i = 0; _i < 2; ++_i) \
;         __builtin_amdgcn_global_load_lds((const unsigned*)((const char*)(gbase) + (voff)[_i]), (PG8_LAS unsigned*)(lds + (bufoff) + ldsw + _i * 8192), 16, 0, 0); } while (0)
; #define PG8_LDA(dst, b, h) do { _Pragma("unroll") for (int m = 0; m < 4; ++m) _Pragma("unroll") for (int k = 0; k < 2; ++k) dst[m][k] = *(const PG8_LAS bf16x8*)(lds + PG8_SA(b, h) + aoff + m * 2048 + k * 1024); } while (0)
; #define PG8_LDB(dst, b, h) do { _Pragma("unroll") for (int n = 0; n < 2; ++n) _Pragma("unroll") for (int k = 0; k < 2; ++k) dst[n][k] = *(const PG8_LAS bf16x8*)(lds + PG8_SB(b, h) + boff + n * 2048 + k * 1024); } while (0)
; #define PG8_MMA(ai, bj, At, Bt) do { __builtin_amdgcn_s_setprio(1); _Pragma("unroll") for (int m = 0; m < 4; ++m) _Pragma("unroll") for (int n = 0; n < 2; ++n) _Pragma("unroll") for (int k = 0; k < 2; ++k) \
;         acc[ai][bj][m][n] = __builtin_amdgcn_mfma_f32_16x16x32_bf16(Bt[n][k], At[m][k], acc[ai][bj][m][n], 0, 0, 0); __builtin_amdgcn_s_setprio(0); } while (0)
; #define PG8_WAIT_V(n) asm volatile("s_waitcnt vmcnt(" #n ")" ::: "memory")
; #define PG8_WAIT_L(n) asm volatile("s_waitcnt lgkmcnt(" #n ")" ::: "memory")
; #define PG8_BAR __builtin_amdgcn_s_barrier()
; #define PG8_SCHED __builtin_amdgcn_sched_barrier(0)
; template <class Epi, class Sched, bool ALIGN_EPI = false, bool SP2 = false>
; __device__ __forceinline__ void gemm_phase(PG8_LAS unsigned char* lds, const Gemm g, const Sched& S, const Epi& E) {
;     ...
;             PG8_LDB(B0, 0, 0); PG8_LDB(B1, 0, 1); PG8_SCHED; PG8_LDA(At, 0, 0); PG8_STAGE(PG8_SA(1, 1), a1 + hstep, voffA);
;             PG8_WAIT_V(8); PG8_WAIT_L(0); PG8_BAR; PG8_MMA(0, 0, At, B0); if (doB1) PG8_MMA(0, 1, At, B1); PG8_BAR; PG8_SCHED;
.LBB0_366:
	s_waitcnt lgkmcnt(0)
	v_add_u32_e32 v112, 0x10000, v228
	ds_read_b128 v[154:157], v112
	ds_read_b128 v[158:161], v112 offset:1024
	ds_read_b128 v[162:165], v112 offset:2048
	ds_read_b128 v[166:169], v112 offset:3072
	v_add_u32_e32 v112, 0x14000, v228
	ds_read_b128 v[130:133], v112
	ds_read_b128 v[134:137], v112 offset:1024
	ds_read_b128 v[146:149], v112 offset:2048
	ds_read_b128 v[150:153], v112 offset:3072
	v_lshl_add_u64 v[112:113], s[72:73], 0, v[214:215]
	s_add_i32 m0, s16, 0xc000
	ds_read_b128 v[194:197], v229
	ds_read_b128 v[198:201], v229 offset:1024
	ds_read_b128 v[186:189], v229 offset:2048
	ds_read_b128 v[190:193], v229 offset:3072
	ds_read_b128 v[178:181], v229 offset:4096
	ds_read_b128 v[182:185], v229 offset:5120
	ds_read_b128 v[170:173], v229 offset:6144
	ds_read_b128 v[174:177], v229 offset:7168
	global_load_lds_dwordx4 v[112:113], off
	v_lshl_add_u64 v[112:113], s[72:73], 0, v[216:217]
	s_add_i32 m0, s16, 0xe000
	s_nop 0
	global_load_lds_dwordx4 v[112:113], off
	s_waitcnt vmcnt(8)
	s_waitcnt lgkmcnt(0)
	s_barrier
	s_setprio 1
	v_mfma_f32_16x16x32_bf16 v[112:115], v[154:157], v[194:197], v[142:145]
	v_mfma_f32_16x16x32_bf16 v[116:119], v[162:165], v[194:197], v[138:141]
	v_mfma_f32_16x16x32_bf16 v[124:127], v[154:157], v[186:189], v[124:127]
	v_mfma_f32_16x16x32_bf16 v[120:123], v[162:165], v[186:189], v[120:123]
	v_mfma_f32_16x16x32_bf16 v[108:111], v[154:157], v[178:181], v[108:111]
	v_mfma_f32_16x16x32_bf16 v[104:107], v[162:165], v[178:181], v[104:107]
	v_mfma_f32_16x16x32_bf16 v[100:103], v[154:157], v[170:173], v[100:103]
	v_mfma_f32_16x16x32_bf16 v[96:99], v[162:165], v[170:173], v[96:99]
	v_mfma_f32_16x16x32_bf16 v[112:115], v[158:161], v[198:201], v[112:115]
	v_mfma_f32_16x16x32_bf16 v[116:119], v[166:169], v[198:201], v[116:119]
	v_mfma_f32_16x16x32_bf16 v[124:127], v[158:161], v[190:193], v[124:127]
	v_mfma_f32_16x16x32_bf16 v[120:123], v[166:169], v[190:193], v[120:123]
	v_mfma_f32_16x16x32_bf16 v[108:111], v[158:161], v[182:185], v[108:111]
	v_mfma_f32_16x16x32_bf16 v[104:107], v[166:169], v[182:185], v[104:107]
	v_mfma_f32_16x16x32_bf16 v[100:103], v[158:161], v[174:177], v[100:103]
	v_mfma_f32_16x16x32_bf16 v[96:99], v[166:169], v[174:177], v[96:99]
	s_setprio 0
	v_cndmask_b32_e64 v128, 0, 1, s[66:67]
	v_cmp_ne_u32_e64 s[6:7], 1, v128
	s_andn2_b64 vcc, exec, s[66:67]
	s_cbranch_vccnz .LBB0_368
	s_setprio 1
	v_mfma_f32_16x16x32_bf16 v[92:95], v[130:133], v[194:197], v[92:95]
	v_mfma_f32_16x16x32_bf16 v[88:91], v[146:149], v[194:197], v[88:91]
	v_mfma_f32_16x16x32_bf16 v[84:87], v[130:133], v[186:189], v[84:87]
	v_mfma_f32_16x16x32_bf16 v[80:83], v[146:149], v[186:189], v[80:83]
	v_mfma_f32_16x16x32_bf16 v[76:79], v[130:133], v[178:181], v[76:79]
	v_mfma_f32_16x16x32_bf16 v[72:75], v[146:149], v[178:181], v[72:75]
	v_mfma_f32_16x16x32_bf16 v[68:71], v[130:133], v[170:173], v[68:71]
	v_mfma_f32_16x16x32_bf16 v[64:67], v[146:149], v[170:173], v[64:67]
	v_mfma_f32_16x16x32_bf16 v[92:95], v[134:137], v[198:201], v[92:95]
	v_mfma_f32_16x16x32_bf16 v[88:91], v[150:153], v[198:201], v[88:91]
	v_mfma_f32_16x16x32_bf16 v[84:87], v[134:137], v[190:193], v[84:87]
	v_mfma_f32_16x16x32_bf16 v[80:83], v[150:153], v[190:193], v[80:83]
	v_mfma_f32_16x16x32_bf16 v[76:79], v[134:137], v[182:185], v[76:79]
	v_mfma_f32_16x16x32_bf16 v[72:75], v[150:153], v[182:185], v[72:75]
	v_mfma_f32_16x16x32_bf16 v[68:71], v[134:137], v[174:177], v[68:71]
	v_mfma_f32_16x16x32_bf16 v[64:67], v[150:153], v[174:177], v[64:67]
	s_setprio 0

; #define PG8_STAGE(bufoff, gbase, voff) do { _Pragma("unroll") for (int _i = 0; _i < 2; ++_i) \
;         __builtin_amdgcn_global_load_lds((const unsigned*)((const char*)(gbase) + (voff)[_i]), (PG8_LAS unsigned*)(lds + (bufoff) + ldsw + _i * 8192), 16, 0, 0); } while (0)
; #define PG8_LDA(dst, b, h) do { _Pragma("unroll") for (int m = 0; m < 4; ++m) _Pragma("unroll") for (int k = 0; k < 2; ++k) dst[m][k] = *(const PG8_LAS bf16x8*)(lds + PG8_SA(b, h) + aoff + m * 2048 + k * 1024); } while (0)
; #define PG8_LDB(dst, b, h) do { _Pragma("unroll") for (int n = 0; n < 2; ++n) _Pragma("unroll") for (int k = 0; k < 2; ++k) dst[n][k] = *(const PG8_LAS bf16x8*)(lds + PG8_SB(b, h) + boff + n * 2048 + k * 1024); } while (0)
; #define PG8_MMA(ai, bj, At, Bt) do { __builtin_amdgcn_s_setprio(1); _Pragma("unroll") for (int m = 0; m < 4; ++m) _Pragma("unroll") for (int n = 0; n < 2; ++n) _Pragma("unroll") for (int k = 0; k < 2; ++k) \
;         acc[ai][bj][m][n] = __builtin_amdgcn_mfma_f32_16x16x32_bf16(Bt[n][k], At[m][k], acc[ai][bj][m][n], 0, 0, 0); __builtin_amdgcn_s_setprio(0); } while (0)
; #define PG8_WAIT_V(n) asm volatile("s_waitcnt vmcnt(" #n ")" ::: "memory")
; #define PG8_WAIT_L(n) asm volatile("s_waitcnt lgkmcnt(" #n ")" ::: "memory")
; #define PG8_BAR __builtin_amdgcn_s_barrier()
; #define PG8_SCHED __builtin_amdgcn_sched_barrier(0)
; template <class Epi, class Sched, bool ALIGN_EPI = false, bool SP2 = false>
; __device__ __forceinline__ void gemm_phase(PG8_LAS unsigned char* lds, const Gemm g, const Sched& S, const Epi& E) {
;     ...
;             PG8_LDB(B0, 1, 0); PG8_LDB(B1, 1, 1); PG8_SCHED; PG8_LDA(At, 1, 0); PG8_STAGE(PG8_SA(0, 1), a2 + hstep, voffA);
;             PG8_WAIT_V(8); PG8_WAIT_L(0); PG8_BAR; PG8_MMA(0, 0, At, B0); if (doB1) PG8_MMA(0, 1, At, B1); PG8_BAR; PG8_SCHED;
.LBB0_371:
	s_barrier
	v_add_u32_e32 v128, 0x18000, v228
	ds_read_b128 v[154:157], v128
	ds_read_b128 v[158:161], v128 offset:1024
	ds_read_b128 v[162:165], v128 offset:2048
	ds_read_b128 v[166:169], v128 offset:3072
	v_add_u32_e32 v128, 0x1c000, v228
	ds_read_b128 v[130:133], v128
	ds_read_b128 v[134:137], v128 offset:1024
	ds_read_b128 v[146:149], v128 offset:2048
	ds_read_b128 v[150:153], v128 offset:3072
	s_add_u32 s94, s94, 0x40000
	s_addc_u32 s95, s95, 0
	s_mov_b32 m0, s27
	s_waitcnt lgkmcnt(0)
	v_lshl_add_u64 v[138:139], s[94:95], 0, v[202:203]
	ds_read_b128 v[194:197], v229 offset:32768
	ds_read_b128 v[198:201], v229 offset:33792
	ds_read_b128 v[186:189], v229 offset:34816
	ds_read_b128 v[190:193], v229 offset:35840
	ds_read_b128 v[178:181], v229 offset:36864
	ds_read_b128 v[182:185], v229 offset:37888
	ds_read_b128 v[170:173], v229 offset:38912
	ds_read_b128 v[174:177], v229 offset:39936
	global_load_lds_dwordx4 v[138:139], off
	v_lshl_add_u64 v[138:139], s[94:95], 0, v[206:207]
	s_mov_b32 m0, s28
	s_nop 0
	global_load_lds_dwordx4 v[138:139], off
	s_waitcnt vmcnt(8)
	s_waitcnt lgkmcnt(0)
	s_barrier
	s_setprio 1
	v_mfma_f32_16x16x32_bf16 v[112:115], v[154:157], v[194:197], v[112:115]
	v_mfma_f32_16x16x32_bf16 v[142:145], v[158:161], v[198:201], v[112:115]
	v_mfma_f32_16x16x32_bf16 v[112:115], v[162:165], v[194:197], v[116:119]
	v_mfma_f32_16x16x32_bf16 v[138:141], v[166:169], v[198:201], v[112:115]
	v_mfma_f32_16x16x32_bf16 v[112:115], v[154:157], v[186:189], v[124:127]
	v_mfma_f32_16x16x32_bf16 v[124:127], v[158:161], v[190:193], v[112:115]
	v_mfma_f32_16x16x32_bf16 v[112:115], v[162:165], v[186:189], v[120:123]
	v_mfma_f32_16x16x32_bf16 v[108:111], v[154:157], v[178:181], v[108:111]
	v_mfma_f32_16x16x32_bf16 v[104:107], v[162:165], v[178:181], v[104:107]
	v_mfma_f32_16x16x32_bf16 v[100:103], v[154:157], v[170:173], v[100:103]
	v_mfma_f32_16x16x32_bf16 v[96:99], v[162:165], v[170:173], v[96:99]
	v_mfma_f32_16x16x32_bf16 v[120:123], v[166:169], v[190:193], v[112:115]
	v_mfma_f32_16x16x32_bf16 v[108:111], v[158:161], v[182:185], v[108:111]
	v_mfma_f32_16x16x32_bf16 v[104:107], v[166:169], v[182:185], v[104:107]
	v_mfma_f32_16x16x32_bf16 v[100:103], v[158:161], v[174:177], v[100:103]
	v_mfma_f32_16x16x32_bf16 v[96:99], v[166:169], v[174:177], v[96:99]
	s_setprio 0
	s_and_b64 vcc, exec, s[6:7]
	s_cbranch_vccnz .LBB0_373
	s_setprio 1
	v_mfma_f32_16x16x32_bf16 v[92:95], v[130:133], v[194:197], v[92:95]
	v_mfma_f32_16x16x32_bf16 v[88:91], v[146:149], v[194:197], v[88:91]
	v_mfma_f32_16x16x32_bf16 v[84:87], v[130:133], v[186:189], v[84:87]
	v_mfma_f32_16x16x32_bf16 v[80:83], v[146:149], v[186:189], v[80:83]
	v_mfma_f32_16x16x32_bf16 v[76:79], v[130:133], v[178:181], v[76:79]
	v_mfma_f32_16x16x32_bf16 v[72:75], v[146:149], v[178:181], v[72:75]
	v_mfma_f32_16x16x32_bf16 v[68:71], v[130:133], v[170:173], v[68:71]
	v_mfma_f32_16x16x32_bf16 v[64:67], v[146:149], v[170:173], v[64:67]
	v_mfma_f32_16x16x32_bf16 v[92:95], v[134:137], v[198:201], v[92:95]
	v_mfma_f32_16x16x32_bf16 v[88:91], v[150:153], v[198:201], v[88:91]
	v_mfma_f32_16x16x32_bf16 v[84:87], v[134:137], v[190:193], v[84:87]
	v_mfma_f32_16x16x32_bf16 v[80:83], v[150:153], v[190:193], v[80:83]
	v_mfma_f32_16x16x32_bf16 v[76:79], v[134:137], v[182:185], v[76:79]
	v_mfma_f32_16x16x32_bf16 v[72:75], v[150:153], v[182:185], v[72:75]
	v_mfma_f32_16x16x32_bf16 v[68:71], v[134:137], v[174:177], v[68:71]
	v_mfma_f32_16x16x32_bf16 v[64:67], v[150:153], v[174:177], v[64:67]
	s_setprio 0

; #define PG8_STAGE(bufoff, gbase, voff) do { _Pragma("unroll") for (int _i = 0; _i < 2; ++_i) \
;         __builtin_amdgcn_global_load_lds((const unsigned*)((const char*)(gbase) + (voff)[_i]), (PG8_LAS unsigned*)(lds + (bufoff) + ldsw + _i * 8192), 16, 0, 0); } while (0)
; #define PG8_LDA(dst, b, h) do { _Pragma("unroll") for (int m = 0; m < 4; ++m) _Pragma("unroll") for (int k = 0; k < 2; ++k) dst[m][k] = *(const PG8_LAS bf16x8*)(lds + PG8_SA(b, h) + aoff + m * 2048 + k * 1024); } while (0)
; #define PG8_LDB(dst, b, h) do { _Pragma("unroll") for (int n = 0; n < 2; ++n) _Pragma("unroll") for (int k = 0; k < 2; ++k) dst[n][k] = *(const PG8_LAS bf16x8*)(lds + PG8_SB(b, h) + boff + n * 2048 + k * 1024); } while (0)
; #define PG8_MMA(ai, bj, At, Bt) do { __builtin_amdgcn_s_setprio(1); _Pragma("unroll") for (int m = 0; m < 4; ++m) _Pragma("unroll") for (int n = 0; n < 2; ++n) _Pragma("unroll") for (int k = 0; k < 2; ++k) \
;         acc[ai][bj][m][n] = __builtin_amdgcn_mfma_f32_16x16x32_bf16(Bt[n][k], At[m][k], acc[ai][bj][m][n], 0, 0, 0); __builtin_amdgcn_s_setprio(0); } while (0)
; #define PG8_WAIT_V(n) asm volatile("s_waitcnt vmcnt(" #n ")" ::: "memory")
; #define PG8_WAIT_L(n) asm volatile("s_waitcnt lgkmcnt(" #n ")" ::: "memory")
; #define PG8_BAR __builtin_amdgcn_s_barrier()
; #define PG8_SCHED __builtin_amdgcn_sched_barrier(0)
; template <class Epi, class Sched, bool ALIGN_EPI = false, bool SP2 = false>
; __device__ __forceinline__ void gemm_phase(PG8_LAS unsigned char* lds, const Gemm g, const Sched& S, const Epi& E) {
;     ...
;             PG8_LDB(B0, 0, 0); PG8_LDB(B1, 0, 1); PG8_SCHED; PG8_LDA(At, 0, 0); PG8_STAGE(PG8_SA(1, 1), a1 + hstep, voffA);
;             PG8_WAIT_V(8); PG8_WAIT_L(0); PG8_BAR; PG8_MMA(0, 0, At, B0); if (doB1) PG8_MMA(0, 1, At, B1); PG8_BAR; PG8_SCHED;
.LBB0_428:
	s_waitcnt lgkmcnt(0)
	v_add_u32_e32 v96, 0x10000, v247
	ds_read_b128 v[162:165], v96
	ds_read_b128 v[166:169], v96 offset:1024
	ds_read_b128 v[170:173], v96 offset:2048
	ds_read_b128 v[174:177], v96 offset:3072
	v_add_u32_e32 v96, 0x14000, v247
	ds_read_b128 v[146:149], v96
	ds_read_b128 v[150:153], v96 offset:1024
	ds_read_b128 v[154:157], v96 offset:2048
	ds_read_b128 v[158:161], v96 offset:3072
	v_lshl_add_u64 v[96:97], s[72:73], 0, v[222:223]
	s_add_i32 m0, s16, 0xc000
	ds_read_b128 v[202:205], v248
	ds_read_b128 v[206:209], v248 offset:1024
	ds_read_b128 v[194:197], v248 offset:2048
	ds_read_b128 v[198:201], v248 offset:3072
	ds_read_b128 v[186:189], v248 offset:4096
	ds_read_b128 v[190:193], v248 offset:5120
	ds_read_b128 v[178:181], v248 offset:6144
	ds_read_b128 v[182:185], v248 offset:7168
	global_load_lds_dwordx4 v[96:97], off
	v_lshl_add_u64 v[96:97], s[72:73], 0, v[224:225]
	s_add_i32 m0, s16, 0xe000
	s_nop 0
	global_load_lds_dwordx4 v[96:97], off
	s_waitcnt vmcnt(8)
	s_waitcnt lgkmcnt(0)
	s_barrier
	s_setprio 1
	v_mfma_f32_16x16x32_bf16 v[96:99], v[162:165], v[202:205], v[142:145]
	v_mfma_f32_16x16x32_bf16 v[100:103], v[170:173], v[202:205], v[138:141]
	v_mfma_f32_16x16x32_bf16 v[104:107], v[162:165], v[194:197], v[134:137]
	v_mfma_f32_16x16x32_bf16 v[108:111], v[170:173], v[194:197], v[130:133]
	v_mfma_f32_16x16x32_bf16 v[116:119], v[162:165], v[186:189], v[116:119]
	v_mfma_f32_16x16x32_bf16 v[112:115], v[170:173], v[186:189], v[112:115]
	v_mfma_f32_16x16x32_bf16 v[92:95], v[162:165], v[178:181], v[92:95]
	v_mfma_f32_16x16x32_bf16 v[88:91], v[170:173], v[178:181], v[88:91]
	v_mfma_f32_16x16x32_bf16 v[96:99], v[166:169], v[206:209], v[96:99]
	v_mfma_f32_16x16x32_bf16 v[100:103], v[174:177], v[206:209], v[100:103]
	v_mfma_f32_16x16x32_bf16 v[104:107], v[166:169], v[198:201], v[104:107]
	v_mfma_f32_16x16x32_bf16 v[108:111], v[174:177], v[198:201], v[108:111]
	v_mfma_f32_16x16x32_bf16 v[116:119], v[166:169], v[190:193], v[116:119]
	v_mfma_f32_16x16x32_bf16 v[112:115], v[174:177], v[190:193], v[112:115]
	v_mfma_f32_16x16x32_bf16 v[92:95], v[166:169], v[182:185], v[92:95]
	v_mfma_f32_16x16x32_bf16 v[88:91], v[174:177], v[182:185], v[88:91]
	s_setprio 0
	v_cndmask_b32_e64 v128, 0, 1, s[66:67]
	v_cmp_ne_u32_e64 s[8:9], 1, v128
	s_andn2_b64 vcc, exec, s[66:67]
	s_cbranch_vccnz .LBB0_430
	s_setprio 1
	v_mfma_f32_16x16x32_bf16 v[124:127], v[146:149], v[202:205], v[124:127]
	v_mfma_f32_16x16x32_bf16 v[120:123], v[154:157], v[202:205], v[120:123]
	v_mfma_f32_16x16x32_bf16 v[84:87], v[146:149], v[194:197], v[84:87]
	v_mfma_f32_16x16x32_bf16 v[80:83], v[154:157], v[194:197], v[80:83]
	v_mfma_f32_16x16x32_bf16 v[76:79], v[146:149], v[186:189], v[76:79]
	v_mfma_f32_16x16x32_bf16 v[72:75], v[154:157], v[186:189], v[72:75]
	v_mfma_f32_16x16x32_bf16 v[68:71], v[146:149], v[178:181], v[68:71]
	v_mfma_f32_16x16x32_bf16 v[64:67], v[154:157], v[178:181], v[64:67]
	v_mfma_f32_16x16x32_bf16 v[124:127], v[150:153], v[206:209], v[124:127]
	v_mfma_f32_16x16x32_bf16 v[120:123], v[158:161], v[206:209], v[120:123]
	v_mfma_f32_16x16x32_bf16 v[84:87], v[150:153], v[198:201], v[84:87]
	v_mfma_f32_16x16x32_bf16 v[80:83], v[158:161], v[198:201], v[80:83]
	v_mfma_f32_16x16x32_bf16 v[76:79], v[150:153], v[190:193], v[76:79]
	v_mfma_f32_16x16x32_bf16 v[72:75], v[158:161], v[190:193], v[72:75]
	v_mfma_f32_16x16x32_bf16 v[68:71], v[150:153], v[182:185], v[68:71]
	v_mfma_f32_16x16x32_bf16 v[64:67], v[158:161], v[182:185], v[64:67]
	s_setprio 0

; #define PG8_STAGE(bufoff, gbase, voff) do { _Pragma("unroll") for (int _i = 0; _i < 2; ++_i) \
;         __builtin_amdgcn_global_load_lds((const unsigned*)((const char*)(gbase) + (voff)[_i]), (PG8_LAS unsigned*)(lds + (bufoff) + ldsw + _i * 8192), 16, 0, 0); } while (0)
; #define PG8_LDA(dst, b, h) do { _Pragma("unroll") for (int m = 0; m < 4; ++m) _Pragma("unroll") for (int k = 0; k < 2; ++k) dst[m][k] = *(const PG8_LAS bf16x8*)(lds + PG8_SA(b, h) + aoff + m * 2048 + k * 1024); } while (0)
; #define PG8_LDB(dst, b, h) do { _Pragma("unroll") for (int n = 0; n < 2; ++n) _Pragma("unroll") for (int k = 0; k < 2; ++k) dst[n][k] = *(const PG8_LAS bf16x8*)(lds + PG8_SB(b, h) + boff + n * 2048 + k * 1024); } while (0)
; #define PG8_MMA(ai, bj, At, Bt) do { __builtin_amdgcn_s_setprio(1); _Pragma("unroll") for (int m = 0; m < 4; ++m) _Pragma("unroll") for (int n = 0; n < 2; ++n) _Pragma("unroll") for (int k = 0; k < 2; ++k) \
;         acc[ai][bj][m][n] = __builtin_amdgcn_mfma_f32_16x16x32_bf16(Bt[n][k], At[m][k], acc[ai][bj][m][n], 0, 0, 0); __builtin_amdgcn_s_setprio(0); } while (0)
; #define PG8_WAIT_V(n) asm volatile("s_waitcnt vmcnt(" #n ")" ::: "memory")
; #define PG8_WAIT_L(n) asm volatile("s_waitcnt lgkmcnt(" #n ")" ::: "memory")
; #define PG8_BAR __builtin_amdgcn_s_barrier()
; #define PG8_SCHED __builtin_amdgcn_sched_barrier(0)
; template <class Epi, class Sched, bool ALIGN_EPI = false, bool SP2 = false>
; __device__ __forceinline__ void gemm_phase(PG8_LAS unsigned char* lds, const Gemm g, const Sched& S, const Epi& E) {
;     ...
;             PG8_LDB(B0, 1, 0); PG8_LDB(B1, 1, 1); PG8_SCHED; PG8_LDA(At, 1, 0); PG8_STAGE(PG8_SA(0, 1), a2 + hstep, voffA);
;             PG8_WAIT_V(8); PG8_WAIT_L(0); PG8_BAR; PG8_MMA(0, 0, At, B0); if (doB1) PG8_MMA(0, 1, At, B1); PG8_BAR; PG8_SCHED;
.LBB0_433:
	s_barrier
	v_add_u32_e32 v128, 0x18000, v247
	ds_read_b128 v[162:165], v128
	ds_read_b128 v[166:169], v128 offset:1024
	ds_read_b128 v[170:173], v128 offset:2048
	ds_read_b128 v[174:177], v128 offset:3072
	v_add_u32_e32 v128, 0x1c000, v247
	ds_read_b128 v[146:149], v128
	ds_read_b128 v[150:153], v128 offset:1024
	ds_read_b128 v[154:157], v128 offset:2048
	ds_read_b128 v[158:161], v128 offset:3072
	s_add_u32 s94, s94, 0x40000
	s_addc_u32 s95, s95, 0
	s_mov_b32 m0, s27
	s_waitcnt lgkmcnt(0)
	v_lshl_add_u64 v[130:131], s[94:95], 0, v[214:215]
	ds_read_b128 v[202:205], v248 offset:32768
	ds_read_b128 v[206:209], v248 offset:33792
	ds_read_b128 v[194:197], v248 offset:34816
	ds_read_b128 v[198:201], v248 offset:35840
	ds_read_b128 v[186:189], v248 offset:36864
	ds_read_b128 v[190:193], v248 offset:37888
	ds_read_b128 v[178:181], v248 offset:38912
	ds_read_b128 v[182:185], v248 offset:39936
	global_load_lds_dwordx4 v[130:131], off
	v_lshl_add_u64 v[130:131], s[94:95], 0, v[218:219]
	s_mov_b32 m0, s28
	s_nop 0
	global_load_lds_dwordx4 v[130:131], off
	s_waitcnt vmcnt(8)
	s_waitcnt lgkmcnt(0)
	s_barrier
	s_setprio 1
	v_mfma_f32_16x16x32_bf16 v[96:99], v[162:165], v[202:205], v[96:99]
	v_mfma_f32_16x16x32_bf16 v[142:145], v[166:169], v[206:209], v[96:99]
	v_mfma_f32_16x16x32_bf16 v[96:99], v[170:173], v[202:205], v[100:103]
	v_mfma_f32_16x16x32_bf16 v[138:141], v[174:177], v[206:209], v[96:99]
	v_mfma_f32_16x16x32_bf16 v[96:99], v[162:165], v[194:197], v[104:107]
	v_mfma_f32_16x16x32_bf16 v[134:137], v[166:169], v[198:201], v[96:99]
	v_mfma_f32_16x16x32_bf16 v[96:99], v[170:173], v[194:197], v[108:111]
	v_mfma_f32_16x16x32_bf16 v[130:133], v[174:177], v[198:201], v[96:99]
	v_mfma_f32_16x16x32_bf16 v[96:99], v[162:165], v[186:189], v[116:119]
	v_mfma_f32_16x16x32_bf16 v[116:119], v[166:169], v[190:193], v[96:99]
	v_mfma_f32_16x16x32_bf16 v[96:99], v[170:173], v[186:189], v[112:115]
	v_mfma_f32_16x16x32_bf16 v[92:95], v[162:165], v[178:181], v[92:95]
	v_mfma_f32_16x16x32_bf16 v[88:91], v[170:173], v[178:181], v[88:91]
	v_mfma_f32_16x16x32_bf16 v[112:115], v[174:177], v[190:193], v[96:99]
	v_mfma_f32_16x16x32_bf16 v[92:95], v[166:169], v[182:185], v[92:95]
	v_mfma_f32_16x16x32_bf16 v[88:91], v[174:177], v[182:185], v[88:91]
	s_setprio 0
	s_and_b64 vcc, exec, s[8:9]
	s_cbranch_vccnz .LBB0_435
	s_setprio 1
	v_mfma_f32_16x16x32_bf16 v[96:99], v[146:149], v[202:205], v[124:127]
	v_mfma_f32_16x16x32_bf16 v[124:127], v[150:153], v[206:209], v[96:99]
	v_mfma_f32_16x16x32_bf16 v[96:99], v[154:157], v[202:205], v[120:123]
	v_mfma_f32_16x16x32_bf16 v[84:87], v[146:149], v[194:197], v[84:87]
	v_mfma_f32_16x16x32_bf16 v[80:83], v[154:157], v[194:197], v[80:83]
	v_mfma_f32_16x16x32_bf16 v[76:79], v[146:149], v[186:189], v[76:79]
	v_mfma_f32_16x16x32_bf16 v[72:75], v[154:157], v[186:189], v[72:75]
	v_mfma_f32_16x16x32_bf16 v[68:71], v[146:149], v[178:181], v[68:71]
	v_mfma_f32_16x16x32_bf16 v[64:67], v[154:157], v[178:181], v[64:67]
	v_mfma_f32_16x16x32_bf16 v[120:123], v[158:161], v[206:209], v[96:99]
	v_mfma_f32_16x16x32_bf16 v[84:87], v[150:153], v[198:201], v[84:87]
	v_mfma_f32_16x16x32_bf16 v[80:83], v[158:161], v[198:201], v[80:83]
	v_mfma_f32_16x16x32_bf16 v[76:79], v[150:153], v[190:193], v[76:79]
	v_mfma_f32_16x16x32_bf16 v[72:75], v[158:161], v[190:193], v[72:75]
	v_mfma_f32_16x16x32_bf16 v[68:71], v[150:153], v[182:185], v[68:71]
	v_mfma_f32_16x16x32_bf16 v[64:67], v[158:161], v[182:185], v[64:67]
	s_setprio 0

; #define PG8_STAGE(bufoff, gbase, voff) do { _Pragma("unroll") for (int _i = 0; _i < 2; ++_i) \
;         __builtin_amdgcn_global_load_lds((const unsigned*)((const char*)(gbase) + (voff)[_i]), (PG8_LAS unsigned*)(lds + (bufoff) + ldsw + _i * 8192), 16, 0, 0); } while (0)
; #define PG8_LDA(dst, b, h) do { _Pragma("unroll") for (int m = 0; m < 4; ++m) _Pragma("unroll") for (int k = 0; k < 2; ++k) dst[m][k] = *(const PG8_LAS bf16x8*)(lds + PG8_SA(b, h) + aoff + m * 2048 + k * 1024); } while (0)
; #define PG8_LDB(dst, b, h) do { _Pragma("unroll") for (int n = 0; n < 2; ++n) _Pragma("unroll") for (int k = 0; k < 2; ++k) dst[n][k] = *(const PG8_LAS bf16x8*)(lds + PG8_SB(b, h) + boff + n * 2048 + k * 1024); } while (0)
; #define PG8_MMA(ai, bj, At, Bt) do { __builtin_amdgcn_s_setprio(1); _Pragma("unroll") for (int m = 0; m < 4; ++m) _Pragma("unroll") for (int n = 0; n < 2; ++n) _Pragma("unroll") for (int k = 0; k < 2; ++k) \
;         acc[ai][bj][m][n] = __builtin_amdgcn_mfma_f32_16x16x32_bf16(Bt[n][k], At[m][k], acc[ai][bj][m][n], 0, 0, 0); __builtin_amdgcn_s_setprio(0); } while (0)
; #define PG8_WAIT_V(n) asm volatile("s_waitcnt vmcnt(" #n ")" ::: "memory")
; #define PG8_WAIT_L(n) asm volatile("s_waitcnt lgkmcnt(" #n ")" ::: "memory")
; #define PG8_BAR __builtin_amdgcn_s_barrier()
; #define PG8_SCHED __builtin_amdgcn_sched_barrier(0)
; template <class Epi, class Sched, bool ALIGN_EPI = false, bool SP2 = false>
; __device__ __forceinline__ void gemm_phase(PG8_LAS unsigned char* lds, const Gemm g, const Sched& S, const Epi& E) {
;     ...
;             PG8_LDB(B0, 0, 0); PG8_LDB(B1, 0, 1); PG8_SCHED; PG8_LDA(At, 0, 0); PG8_STAGE(PG8_SA(1, 1), a1 + hstep, voffA);
;             PG8_WAIT_V(8); PG8_WAIT_L(0); PG8_BAR; PG8_MMA(0, 0, At, B0); if (doB1) PG8_MMA(0, 1, At, B1); PG8_BAR; PG8_SCHED;
.LBB0_847:
	v_add_u32_e32 v128, 0x10000, v234
	ds_read_b128 v[146:149], v128
	ds_read_b128 v[150:153], v128 offset:1024
	ds_read_b128 v[154:157], v128 offset:2048
	ds_read_b128 v[158:161], v128 offset:3072
	v_add_u32_e32 v128, 0x14000, v234
	ds_read_b128 v[130:133], v128
	ds_read_b128 v[134:137], v128 offset:1024
	ds_read_b128 v[138:141], v128 offset:2048
	ds_read_b128 v[142:145], v128 offset:3072
	v_lshl_add_u64 v[214:215], s[60:61], 0, v[206:207]
	s_add_i32 m0, s50, 0xc000
	s_waitcnt lgkmcnt(0)
	ds_read_b128 v[186:189], v235
	ds_read_b128 v[190:193], v235 offset:1024
	ds_read_b128 v[178:181], v235 offset:2048
	ds_read_b128 v[182:185], v235 offset:3072
	ds_read_b128 v[170:173], v235 offset:4096
	ds_read_b128 v[174:177], v235 offset:5120
	ds_read_b128 v[162:165], v235 offset:6144
	ds_read_b128 v[166:169], v235 offset:7168
	global_load_lds_dwordx4 v[214:215], off
	v_lshl_add_u64 v[214:215], s[60:61], 0, v[208:209]
	s_add_i32 m0, s50, 0xe000
	s_nop 0
	global_load_lds_dwordx4 v[214:215], off
	s_waitcnt vmcnt(8)
	s_waitcnt lgkmcnt(0)
	s_barrier
	s_setprio 1
	v_mfma_f32_16x16x32_bf16 v[124:127], v[146:149], v[186:189], v[124:127]
	v_mfma_f32_16x16x32_bf16 v[120:123], v[154:157], v[186:189], v[120:123]
	v_mfma_f32_16x16x32_bf16 v[116:119], v[146:149], v[178:181], v[116:119]
	v_mfma_f32_16x16x32_bf16 v[112:115], v[154:157], v[178:181], v[112:115]
	v_mfma_f32_16x16x32_bf16 v[92:95], v[146:149], v[170:173], v[92:95]
	v_mfma_f32_16x16x32_bf16 v[88:91], v[154:157], v[170:173], v[88:91]
	v_mfma_f32_16x16x32_bf16 v[84:87], v[146:149], v[162:165], v[84:87]
	v_mfma_f32_16x16x32_bf16 v[80:83], v[154:157], v[162:165], v[80:83]
	v_mfma_f32_16x16x32_bf16 v[124:127], v[150:153], v[190:193], v[124:127]
	v_mfma_f32_16x16x32_bf16 v[120:123], v[158:161], v[190:193], v[120:123]
	v_mfma_f32_16x16x32_bf16 v[116:119], v[150:153], v[182:185], v[116:119]
	v_mfma_f32_16x16x32_bf16 v[112:115], v[158:161], v[182:185], v[112:115]
	v_mfma_f32_16x16x32_bf16 v[92:95], v[150:153], v[174:177], v[92:95]
	v_mfma_f32_16x16x32_bf16 v[88:91], v[158:161], v[174:177], v[88:91]
	v_mfma_f32_16x16x32_bf16 v[84:87], v[150:153], v[166:169], v[84:87]
	v_mfma_f32_16x16x32_bf16 v[80:83], v[158:161], v[166:169], v[80:83]
	s_setprio 0
	v_cndmask_b32_e64 v128, 0, 1, s[72:73]
	v_cmp_ne_u32_e64 s[8:9], 1, v128
	s_andn2_b64 vcc, exec, s[72:73]
	s_cbranch_vccnz .LBB0_849
	s_setprio 1
	v_mfma_f32_16x16x32_bf16 v[108:111], v[130:133], v[186:189], v[108:111]
	v_mfma_f32_16x16x32_bf16 v[104:107], v[138:141], v[186:189], v[104:107]
	v_mfma_f32_16x16x32_bf16 v[100:103], v[130:133], v[178:181], v[100:103]
	v_mfma_f32_16x16x32_bf16 v[96:99], v[138:141], v[178:181], v[96:99]
	v_mfma_f32_16x16x32_bf16 v[76:79], v[130:133], v[170:173], v[76:79]
	v_mfma_f32_16x16x32_bf16 v[72:75], v[138:141], v[170:173], v[72:75]
	v_mfma_f32_16x16x32_bf16 v[68:71], v[130:133], v[162:165], v[68:71]
	v_mfma_f32_16x16x32_bf16 v[64:67], v[138:141], v[162:165], v[64:67]
	v_mfma_f32_16x16x32_bf16 v[108:111], v[134:137], v[190:193], v[108:111]
	v_mfma_f32_16x16x32_bf16 v[104:107], v[142:145], v[190:193], v[104:107]
	v_mfma_f32_16x16x32_bf16 v[100:103], v[134:137], v[182:185], v[100:103]
	v_mfma_f32_16x16x32_bf16 v[96:99], v[142:145], v[182:185], v[96:99]
	v_mfma_f32_16x16x32_bf16 v[76:79], v[134:137], v[174:177], v[76:79]
	v_mfma_f32_16x16x32_bf16 v[72:75], v[142:145], v[174:177], v[72:75]
	v_mfma_f32_16x16x32_bf16 v[68:71], v[134:137], v[166:169], v[68:71]
	v_mfma_f32_16x16x32_bf16 v[64:67], v[142:145], v[166:169], v[64:67]
	s_setprio 0

; #define PG8_STAGE(bufoff, gbase, voff) do { _Pragma("unroll") for (int _i = 0; _i < 2; ++_i) \
;         __builtin_amdgcn_global_load_lds((const unsigned*)((const char*)(gbase) + (voff)[_i]), (PG8_LAS unsigned*)(lds + (bufoff) + ldsw + _i * 8192), 16, 0, 0); } while (0)
; #define PG8_LDA(dst, b, h) do { _Pragma("unroll") for (int m = 0; m < 4; ++m) _Pragma("unroll") for (int k = 0; k < 2; ++k) dst[m][k] = *(const PG8_LAS bf16x8*)(lds + PG8_SA(b, h) + aoff + m * 2048 + k * 1024); } while (0)
; #define PG8_LDB(dst, b, h) do { _Pragma("unroll") for (int n = 0; n < 2; ++n) _Pragma("unroll") for (int k = 0; k < 2; ++k) dst[n][k] = *(const PG8_LAS bf16x8*)(lds + PG8_SB(b, h) + boff + n * 2048 + k * 1024); } while (0)
; #define PG8_MMA(ai, bj, At, Bt) do { __builtin_amdgcn_s_setprio(1); _Pragma("unroll") for (int m = 0; m < 4; ++m) _Pragma("unroll") for (int n = 0; n < 2; ++n) _Pragma("unroll") for (int k = 0; k < 2; ++k) \
;         acc[ai][bj][m][n] = __builtin_amdgcn_mfma_f32_16x16x32_bf16(Bt[n][k], At[m][k], acc[ai][bj][m][n], 0, 0, 0); __builtin_amdgcn_s_setprio(0); } while (0)
; #define PG8_WAIT_V(n) asm volatile("s_waitcnt vmcnt(" #n ")" ::: "memory")
; #define PG8_WAIT_L(n) asm volatile("s_waitcnt lgkmcnt(" #n ")" ::: "memory")
; #define PG8_BAR __builtin_amdgcn_s_barrier()
; #define PG8_SCHED __builtin_amdgcn_sched_barrier(0)
; template <class Epi, class Sched, bool ALIGN_EPI = false, bool SP2 = false>
; __device__ __forceinline__ void gemm_phase(PG8_LAS unsigned char* lds, const Gemm g, const Sched& S, const Epi& E) {
;     ...
;             PG8_LDB(B0, 1, 0); PG8_LDB(B1, 1, 1); PG8_SCHED; PG8_LDA(At, 1, 0); PG8_STAGE(PG8_SA(0, 1), a2 + hstep, voffA);
;             PG8_WAIT_V(8); PG8_WAIT_L(0); PG8_BAR; PG8_MMA(0, 0, At, B0); if (doB1) PG8_MMA(0, 1, At, B1); PG8_BAR; PG8_SCHED;
.LBB0_852:
	s_barrier
	v_add_u32_e32 v128, 0x18000, v234
	ds_read_b128 v[146:149], v128
	ds_read_b128 v[150:153], v128 offset:1024
	ds_read_b128 v[154:157], v128 offset:2048
	ds_read_b128 v[158:161], v128 offset:3072
	v_add_u32_e32 v128, 0x1c000, v234
	ds_read_b128 v[130:133], v128
	ds_read_b128 v[134:137], v128 offset:1024
	ds_read_b128 v[138:141], v128 offset:2048
	ds_read_b128 v[142:145], v128 offset:3072
	s_add_u32 s74, s74, s88
	s_addc_u32 s75, s75, 0
	s_mov_b32 m0, s71
	v_lshl_add_u64 v[240:241], s[74:75], 0, v[194:195]
	s_waitcnt lgkmcnt(0)
	ds_read_b128 v[186:189], v235 offset:32768
	ds_read_b128 v[190:193], v235 offset:33792
	ds_read_b128 v[178:181], v235 offset:34816
	ds_read_b128 v[182:185], v235 offset:35840
	ds_read_b128 v[170:173], v235 offset:36864
	ds_read_b128 v[174:177], v235 offset:37888
	ds_read_b128 v[162:165], v235 offset:38912
	ds_read_b128 v[166:169], v235 offset:39936
	global_load_lds_dwordx4 v[240:241], off
	v_lshl_add_u64 v[240:241], s[74:75], 0, v[198:199]
	s_mov_b32 m0, s33
	s_nop 0
	global_load_lds_dwordx4 v[240:241], off
	s_waitcnt vmcnt(8)
	s_waitcnt lgkmcnt(0)
	s_barrier
	s_setprio 1
	v_mfma_f32_16x16x32_bf16 v[124:127], v[146:149], v[186:189], v[124:127]
	v_mfma_f32_16x16x32_bf16 v[120:123], v[154:157], v[186:189], v[120:123]
	v_mfma_f32_16x16x32_bf16 v[116:119], v[146:149], v[178:181], v[116:119]
	v_mfma_f32_16x16x32_bf16 v[112:115], v[154:157], v[178:181], v[112:115]
	v_mfma_f32_16x16x32_bf16 v[92:95], v[146:149], v[170:173], v[92:95]
	v_mfma_f32_16x16x32_bf16 v[88:91], v[154:157], v[170:173], v[88:91]
	v_mfma_f32_16x16x32_bf16 v[84:87], v[146:149], v[162:165], v[84:87]
	v_mfma_f32_16x16x32_bf16 v[80:83], v[154:157], v[162:165], v[80:83]
	v_mfma_f32_16x16x32_bf16 v[124:127], v[150:153], v[190:193], v[124:127]
	v_mfma_f32_16x16x32_bf16 v[120:123], v[158:161], v[190:193], v[120:123]
	v_mfma_f32_16x16x32_bf16 v[116:119], v[150:153], v[182:185], v[116:119]
	v_mfma_f32_16x16x32_bf16 v[112:115], v[158:161], v[182:185], v[112:115]
	v_mfma_f32_16x16x32_bf16 v[92:95], v[150:153], v[174:177], v[92:95]
	v_mfma_f32_16x16x32_bf16 v[88:91], v[158:161], v[174:177], v[88:91]
	v_mfma_f32_16x16x32_bf16 v[84:87], v[150:153], v[166:169], v[84:87]
	v_mfma_f32_16x16x32_bf16 v[80:83], v[158:161], v[166:169], v[80:83]
	s_setprio 0
	s_and_b64 vcc, exec, s[8:9]
	s_cbranch_vccnz .LBB0_854
	s_setprio 1
	v_mfma_f32_16x16x32_bf16 v[108:111], v[130:133], v[186:189], v[108:111]
	v_mfma_f32_16x16x32_bf16 v[104:107], v[138:141], v[186:189], v[104:107]
	v_mfma_f32_16x16x32_bf16 v[100:103], v[130:133], v[178:181], v[100:103]
	v_mfma_f32_16x16x32_bf16 v[96:99], v[138:141], v[178:181], v[96:99]
	v_mfma_f32_16x16x32_bf16 v[76:79], v[130:133], v[170:173], v[76:79]
	v_mfma_f32_16x16x32_bf16 v[72:75], v[138:141], v[170:173], v[72:75]
	v_mfma_f32_16x16x32_bf16 v[68:71], v[130:133], v[162:165], v[68:71]
	v_mfma_f32_16x16x32_bf16 v[64:67], v[138:141], v[162:165], v[64:67]
	v_mfma_f32_16x16x32_bf16 v[108:111], v[134:137], v[190:193], v[108:111]
	v_mfma_f32_16x16x32_bf16 v[104:107], v[142:145], v[190:193], v[104:107]
	v_mfma_f32_16x16x32_bf16 v[100:103], v[134:137], v[182:185], v[100:103]
	v_mfma_f32_16x16x32_bf16 v[96:99], v[142:145], v[182:185], v[96:99]
	v_mfma_f32_16x16x32_bf16 v[76:79], v[134:137], v[174:177], v[76:79]
	v_mfma_f32_16x16x32_bf16 v[72:75], v[142:145], v[174:177], v[72:75]
	v_mfma_f32_16x16x32_bf16 v[68:71], v[134:137], v[166:169], v[68:71]
	v_mfma_f32_16x16x32_bf16 v[64:67], v[142:145], v[166:169], v[64:67]
	s_setprio 0
